# streaming single-use epilogue loads (P6: x, P8: out) marked nt so they do not displace the GEMM operands in L2; code layout identical to previous best
# speedup vs baseline: 1.0042x; 1.0003x over previous
; __device__ __forceinline__ unsigned cvt_pk_bf16(float lo, float hi) { unsigned r; asm volatile("v_cvt_pk_bf16_f32 %0, %1, %2" : "=v"(r) : "v"(lo), "v"(hi)); return r; }
;     __device__ __forceinline__ void operator()(const f32x4 (&acc)[2][2][4][2], const Unit& u, int wr, int wc, int fr, int fq) const {
;     ...
;             for (int m = 0; m < 4; ++m) { const size_t row = (size_t)(row0 + ai * HALF + m * 16); float ss = 0.f;
; #pragma unroll
;                 for (int bj = 0; bj < 2; ++bj) { const int col = u.pn * BM + bj * HALF + wc * 32 + 8 * fq;
;                     const float* xp = x + row * 2048 + col; float* hp = h1 + row * 2048 + col;
;                     const f32x4 a0 = *(const f32x4*)xp + acc[ai][bj][m][0], a1 = *(const f32x4*)(xp + 4) + acc[ai][bj][m][1];
;                     *(f32x4*)hp = a0; *(f32x4*)(hp + 4) = a1;
;                     ss += a0[0] * a0[0] + a0[1] * a0[1] + a0[2] * a0[2] + a0[3] * a0[3] + a1[0] * a1[0] + a1[1] * a1[1] + a1[2] * a1[2] + a1[3] * a1[3];
;                     u32x4 w; w.x = cvt_pk_bf16(a0[0], a0[1]); w.y = cvt_pk_bf16(a0[2], a0[3]); w.z = cvt_pk_bf16(a1[0], a1[1]); w.w = cvt_pk_bf16(a1[2], a1[3]);
;                     *(u32x4*)(h1b + row * 2048 + col) = w; }
;                 ss += __shfl_xor(ss, 16); ss += __shfl_xor(ss, 32);
;                 if (fq == 0) atomicAdd(rowsq + row, ss); }
.LBB0_667:
	v_lshl_add_u32 v148, s30, 8, v150
	v_lshl_or_b32 v144, s40, 8, v152
	v_ashrrev_i32_e32 v149, 31, v148
	v_lshlrev_b64 v[166:167], 13, v[148:149]
	v_ashrrev_i32_e32 v145, 31, v144
	v_lshl_add_u64 v[158:159], s[36:37], 0, v[166:167]
	v_lshlrev_b64 v[146:147], 2, v[144:145]
	v_lshl_add_u64 v[168:169], v[158:159], 0, v[146:147]
	global_load_dwordx4 v[158:161], v[168:169], off nt
	global_load_dwordx4 v[162:165], v[168:169], off offset:16 nt
	v_lshlrev_b64 v[170:171], 12, v[148:149]
	v_lshl_add_u64 v[166:167], s[26:27], 0, v[166:167]
	v_lshl_add_u64 v[170:171], s[10:11], 0, v[170:171]
	v_lshl_add_u64 v[172:173], v[166:167], 0, v[146:147]
	v_lshl_add_u64 v[170:171], v[144:145], 1, v[170:171]
	v_xor_b32_e32 v157, 32, v156
	s_waitcnt vmcnt(0)
	v_pk_add_f32 v[126:127], v[126:127], v[160:161]
	v_pk_add_f32 v[124:125], v[124:125], v[158:159]
	v_pk_add_f32 v[160:161], v[122:123], v[164:165]
	v_pk_add_f32 v[158:159], v[120:121], v[162:163]
	global_store_dwordx4 v[172:173], v[124:127], off
	global_store_dwordx4 v[172:173], v[158:161], off offset:16
	v_cvt_pk_bf16_f32 v120, v124, v125
	v_cvt_pk_bf16_f32 v121, v126, v127
	v_cvt_pk_bf16_f32 v122, v158, v159
	v_cvt_pk_bf16_f32 v123, v160, v161
	global_store_dwordx4 v[170:171], v[120:123], off
	global_load_dwordx4 v[162:165], v[168:169], off offset:512 nt
	s_nop 0
	global_load_dwordx4 v[166:169], v[168:169], off offset:528 nt
	v_mul_f32_e32 v174, v125, v125
	v_fmac_f32_e32 v174, v124, v124
	v_fmac_f32_e32 v174, v126, v126
	v_fmac_f32_e32 v174, v127, v127
	v_and_b32_e32 v121, 64, v156
	v_fmac_f32_e32 v174, v158, v158
	v_xor_b32_e32 v120, 16, v156
	v_add_u32_e32 v121, 64, v121
	v_fmac_f32_e32 v174, v159, v159
	v_cmp_lt_i32_e32 vcc, v120, v121
	v_fmac_f32_e32 v174, v160, v160
	v_fmac_f32_e32 v174, v161, v161
	v_cndmask_b32_e32 v120, v156, v120, vcc
	v_lshlrev_b32_e32 v120, 2, v120
	v_cmp_lt_i32_e32 vcc, v157, v121
	s_waitcnt vmcnt(1)
	v_pk_add_f32 v[116:117], v[116:117], v[162:163]
	s_waitcnt vmcnt(0)
	v_pk_add_f32 v[122:123], v[112:113], v[166:167]
	v_mul_f32_e32 v112, v117, v117
	v_pk_add_f32 v[118:119], v[118:119], v[164:165]
	v_fmac_f32_e32 v112, v116, v116
	v_fmac_f32_e32 v112, v118, v118
	v_fmac_f32_e32 v112, v119, v119
	v_fmac_f32_e32 v112, v122, v122
	v_pk_add_f32 v[124:125], v[114:115], v[168:169]
	v_fmac_f32_e32 v112, v123, v123
	v_fmac_f32_e32 v112, v124, v124
	v_fmac_f32_e32 v112, v125, v125
	v_add_f32_e32 v112, v174, v112
	ds_bpermute_b32 v113, v120, v112
	v_cndmask_b32_e32 v114, v156, v157, vcc
	v_lshlrev_b32_e32 v114, 2, v114
	global_store_dwordx4 v[172:173], v[116:119], off offset:512
	global_store_dwordx4 v[172:173], v[122:125], off offset:528
	s_waitcnt lgkmcnt(0)
	v_add_f32_e32 v112, v112, v113
	ds_bpermute_b32 v113, v114, v112
	v_cvt_pk_bf16_f32 v116, v116, v117
	v_cvt_pk_bf16_f32 v117, v118, v119
	v_cvt_pk_bf16_f32 v118, v122, v123
	v_cvt_pk_bf16_f32 v119, v124, v125
	global_store_dwordx4 v[170:171], v[116:119], off offset:256
	s_and_saveexec_b64 s[30:31], s[0:1]
	s_cbranch_execz .LBB0_669
	v_lshl_add_u64 v[116:117], v[148:149], 2, s[12:13]
	s_waitcnt lgkmcnt(0)
	v_add_f32_e32 v112, v112, v113
	global_atomic_add_f32 v[116:117], v112, off
.LBB0_669:
	s_or_b64 exec, exec, s[30:31]
	v_or_b32_e32 v112, 16, v148
	s_waitcnt lgkmcnt(0)
	v_ashrrev_i32_e32 v113, 31, v112
	v_lshlrev_b64 v[126:127], 13, v[112:113]
	v_lshl_add_u64 v[116:117], s[36:37], 0, v[126:127]
	v_lshl_add_u64 v[158:159], v[116:117], 0, v[146:147]
	global_load_dwordx4 v[116:119], v[158:159], off nt
	global_load_dwordx4 v[122:125], v[158:159], off offset:16 nt
	v_lshlrev_b64 v[160:161], 12, v[112:113]
	v_lshl_add_u64 v[126:127], s[26:27], 0, v[126:127]
	v_lshl_add_u64 v[160:161], s[10:11], 0, v[160:161]
	v_lshl_add_u64 v[126:127], v[126:127], 0, v[146:147]
	v_lshl_add_u64 v[160:161], v[144:145], 1, v[160:161]
	s_waitcnt vmcnt(1)
	v_pk_add_f32 v[110:111], v[110:111], v[118:119]
	v_pk_add_f32 v[108:109], v[108:109], v[116:117]
	s_waitcnt vmcnt(0)
	v_pk_add_f32 v[106:107], v[106:107], v[124:125]
	v_pk_add_f32 v[104:105], v[104:105], v[122:123]
	global_store_dwordx4 v[126:127], v[108:111], off
	global_store_dwordx4 v[126:127], v[104:107], off offset:16
	v_cvt_pk_bf16_f32 v116, v108, v109
	v_cvt_pk_bf16_f32 v117, v110, v111
	v_cvt_pk_bf16_f32 v118, v104, v105
	v_cvt_pk_bf16_f32 v119, v106, v107
	global_store_dwordx4 v[160:161], v[116:119], off
	global_load_dwordx4 v[116:119], v[158:159], off offset:512 nt
	s_nop 0
	global_load_dwordx4 v[122:125], v[158:159], off offset:528 nt
	v_mul_f32_e32 v109, v109, v109
	v_fmac_f32_e32 v109, v108, v108
	v_fmac_f32_e32 v109, v110, v110
	v_fmac_f32_e32 v109, v111, v111
	v_fmac_f32_e32 v109, v104, v104
	v_fmac_f32_e32 v109, v105, v105
	v_fmac_f32_e32 v109, v106, v106
	v_fmac_f32_e32 v109, v107, v107
	s_waitcnt vmcnt(1)
	v_pk_add_f32 v[100:101], v[100:101], v[116:117]
	s_waitcnt vmcnt(0)
	v_pk_add_f32 v[104:105], v[96:97], v[122:123]
	v_mul_f32_e32 v96, v101, v101
	v_pk_add_f32 v[102:103], v[102:103], v[118:119]
	v_fmac_f32_e32 v96, v100, v100
	v_fmac_f32_e32 v96, v102, v102
	v_fmac_f32_e32 v96, v103, v103
	v_fmac_f32_e32 v96, v104, v104
	v_pk_add_f32 v[106:107], v[98:99], v[124:125]
	v_fmac_f32_e32 v96, v105, v105
	v_fmac_f32_e32 v96, v106, v106
	v_fmac_f32_e32 v96, v107, v107
	v_add_f32_e32 v96, v109, v96
	ds_bpermute_b32 v97, v120, v96
	global_store_dwordx4 v[126:127], v[100:103], off offset:512
	global_store_dwordx4 v[126:127], v[104:107], off offset:528
	v_cvt_pk_bf16_f32 v98, v100, v101
	v_cvt_pk_bf16_f32 v99, v102, v103
	s_waitcnt lgkmcnt(0)
	v_add_f32_e32 v96, v96, v97
	ds_bpermute_b32 v97, v114, v96
	v_cvt_pk_bf16_f32 v100, v104, v105
	v_cvt_pk_bf16_f32 v101, v106, v107
	global_store_dwordx4 v[160:161], v[98:101], off offset:256
	s_and_saveexec_b64 s[30:31], s[0:1]
	s_cbranch_execz .LBB0_671
	v_lshl_add_u64 v[98:99], v[112:113], 2, s[12:13]
	s_waitcnt lgkmcnt(0)
	v_add_f32_e32 v96, v96, v97
	global_atomic_add_f32 v[98:99], v96, off
; __device__ __forceinline__ unsigned cvt_pk_bf16(float lo, float hi) { unsigned r; asm volatile("v_cvt_pk_bf16_f32 %0, %1, %2" : "=v"(r) : "v"(lo), "v"(hi)); return r; }
;     __device__ __forceinline__ void operator()(const f32x4 (&acc)[2][2][4][2], const Unit& u, int wr, int wc, int fr, int fq) const {
;     ...
;             for (int m = 0; m < 4; ++m) { const size_t row = (size_t)(row0 + ai * HALF + m * 16); float ss = 0.f;
; #pragma unroll
;                 for (int bj = 0; bj < 2; ++bj) { const int col = u.pn * BM + bj * HALF + wc * 32 + 8 * fq;
;                     const float* xp = x + row * 2048 + col; float* hp = h1 + row * 2048 + col;
;                     const f32x4 a0 = *(const f32x4*)xp + acc[ai][bj][m][0], a1 = *(const f32x4*)(xp + 4) + acc[ai][bj][m][1];
;                     *(f32x4*)hp = a0; *(f32x4*)(hp + 4) = a1;
;                     ss += a0[0] * a0[0] + a0[1] * a0[1] + a0[2] * a0[2] + a0[3] * a0[3] + a1[0] * a1[0] + a1[1] * a1[1] + a1[2] * a1[2] + a1[3] * a1[3];
;                     u32x4 w; w.x = cvt_pk_bf16(a0[0], a0[1]); w.y = cvt_pk_bf16(a0[2], a0[3]); w.z = cvt_pk_bf16(a1[0], a1[1]); w.w = cvt_pk_bf16(a1[2], a1[3]);
;                     *(u32x4*)(h1b + row * 2048 + col) = w; }
;                 ss += __shfl_xor(ss, 16); ss += __shfl_xor(ss, 32);
;                 if (fq == 0) atomicAdd(rowsq + row, ss); }
.LBB0_671:
	s_or_b64 exec, exec, s[30:31]
	v_or_b32_e32 v96, 32, v148
	s_waitcnt lgkmcnt(0)
	v_ashrrev_i32_e32 v97, 31, v96
	v_lshlrev_b64 v[106:107], 13, v[96:97]
	v_lshl_add_u64 v[98:99], s[36:37], 0, v[106:107]
	v_lshl_add_u64 v[108:109], v[98:99], 0, v[146:147]
	global_load_dwordx4 v[98:101], v[108:109], off nt
	global_load_dwordx4 v[102:105], v[108:109], off offset:16 nt
	v_lshlrev_b64 v[110:111], 12, v[96:97]
	v_lshl_add_u64 v[106:107], s[26:27], 0, v[106:107]
	v_lshl_add_u64 v[110:111], s[10:11], 0, v[110:111]
	v_lshl_add_u64 v[106:107], v[106:107], 0, v[146:147]
	v_lshl_add_u64 v[110:111], v[144:145], 1, v[110:111]
	s_waitcnt vmcnt(1)
	v_pk_add_f32 v[94:95], v[94:95], v[100:101]
	v_pk_add_f32 v[92:93], v[92:93], v[98:99]
	s_waitcnt vmcnt(0)
	v_pk_add_f32 v[90:91], v[90:91], v[104:105]
	v_pk_add_f32 v[88:89], v[88:89], v[102:103]
	global_store_dwordx4 v[106:107], v[92:95], off
	global_store_dwordx4 v[106:107], v[88:91], off offset:16
	v_cvt_pk_bf16_f32 v98, v92, v93
	v_cvt_pk_bf16_f32 v99, v94, v95
	v_cvt_pk_bf16_f32 v100, v88, v89
	v_cvt_pk_bf16_f32 v101, v90, v91
	global_store_dwordx4 v[110:111], v[98:101], off
	global_load_dwordx4 v[98:101], v[108:109], off offset:512 nt
	s_nop 0
	global_load_dwordx4 v[102:105], v[108:109], off offset:528 nt
	v_mul_f32_e32 v93, v93, v93
	v_fmac_f32_e32 v93, v92, v92
	v_fmac_f32_e32 v93, v94, v94
	v_fmac_f32_e32 v93, v95, v95
	v_fmac_f32_e32 v93, v88, v88
	v_fmac_f32_e32 v93, v89, v89
	v_fmac_f32_e32 v93, v90, v90
	v_fmac_f32_e32 v93, v91, v91
	s_waitcnt vmcnt(1)
	v_pk_add_f32 v[84:85], v[84:85], v[98:99]
	s_waitcnt vmcnt(0)
	v_pk_add_f32 v[88:89], v[80:81], v[102:103]
	v_mul_f32_e32 v80, v85, v85
	v_pk_add_f32 v[86:87], v[86:87], v[100:101]
	v_fmac_f32_e32 v80, v84, v84
	v_fmac_f32_e32 v80, v86, v86
	v_fmac_f32_e32 v80, v87, v87
	v_fmac_f32_e32 v80, v88, v88
	v_pk_add_f32 v[90:91], v[82:83], v[104:105]
	v_fmac_f32_e32 v80, v89, v89
	v_fmac_f32_e32 v80, v90, v90
	v_fmac_f32_e32 v80, v91, v91
	v_add_f32_e32 v80, v93, v80
	ds_bpermute_b32 v81, v120, v80
	global_store_dwordx4 v[106:107], v[84:87], off offset:512
	global_store_dwordx4 v[106:107], v[88:91], off offset:528
	v_cvt_pk_bf16_f32 v82, v84, v85
	v_cvt_pk_bf16_f32 v83, v86, v87
	s_waitcnt lgkmcnt(0)
	v_add_f32_e32 v80, v80, v81
	ds_bpermute_b32 v81, v114, v80
	v_cvt_pk_bf16_f32 v84, v88, v89
	v_cvt_pk_bf16_f32 v85, v90, v91
	global_store_dwordx4 v[110:111], v[82:85], off offset:256
	s_and_saveexec_b64 s[30:31], s[0:1]
	s_cbranch_execz .LBB0_673
	v_lshl_add_u64 v[82:83], v[96:97], 2, s[12:13]
	s_waitcnt lgkmcnt(0)
	v_add_f32_e32 v80, v80, v81
	global_atomic_add_f32 v[82:83], v80, off
.LBB0_673:
	s_or_b64 exec, exec, s[30:31]
	v_or_b32_e32 v80, 48, v148
	s_waitcnt lgkmcnt(0)
	v_ashrrev_i32_e32 v81, 31, v80
	v_lshlrev_b64 v[90:91], 13, v[80:81]
	v_lshl_add_u64 v[82:83], s[36:37], 0, v[90:91]
	v_lshl_add_u64 v[92:93], v[82:83], 0, v[146:147]
	global_load_dwordx4 v[82:85], v[92:93], off nt
	global_load_dwordx4 v[86:89], v[92:93], off offset:16 nt
	v_lshlrev_b64 v[94:95], 12, v[80:81]
	v_lshl_add_u64 v[90:91], s[26:27], 0, v[90:91]
	v_lshl_add_u64 v[94:95], s[10:11], 0, v[94:95]
	v_lshl_add_u64 v[90:91], v[90:91], 0, v[146:147]
	v_lshl_add_u64 v[94:95], v[144:145], 1, v[94:95]
	s_waitcnt vmcnt(1)
	v_pk_add_f32 v[78:79], v[78:79], v[84:85]
	v_pk_add_f32 v[76:77], v[76:77], v[82:83]
	s_waitcnt vmcnt(0)
	v_pk_add_f32 v[74:75], v[74:75], v[88:89]
	v_pk_add_f32 v[72:73], v[72:73], v[86:87]
	global_store_dwordx4 v[90:91], v[76:79], off
	global_store_dwordx4 v[90:91], v[72:75], off offset:16
	v_cvt_pk_bf16_f32 v82, v76, v77
	v_cvt_pk_bf16_f32 v83, v78, v79
	v_cvt_pk_bf16_f32 v84, v72, v73
	v_cvt_pk_bf16_f32 v85, v74, v75
	global_store_dwordx4 v[94:95], v[82:85], off
	global_load_dwordx4 v[82:85], v[92:93], off offset:512 nt
	s_nop 0
	global_load_dwordx4 v[86:89], v[92:93], off offset:528 nt
	v_mul_f32_e32 v77, v77, v77
	v_fmac_f32_e32 v77, v76, v76
	v_fmac_f32_e32 v77, v78, v78
	v_fmac_f32_e32 v77, v79, v79
	v_fmac_f32_e32 v77, v72, v72
	v_fmac_f32_e32 v77, v73, v73
	v_fmac_f32_e32 v77, v74, v74
	v_fmac_f32_e32 v77, v75, v75
	s_waitcnt vmcnt(1)
	v_pk_add_f32 v[68:69], v[68:69], v[82:83]
	s_waitcnt vmcnt(0)
	v_pk_add_f32 v[72:73], v[64:65], v[86:87]
	v_mul_f32_e32 v64, v69, v69
	v_pk_add_f32 v[70:71], v[70:71], v[84:85]
	v_fmac_f32_e32 v64, v68, v68
	v_fmac_f32_e32 v64, v70, v70
	v_fmac_f32_e32 v64, v71, v71
	v_fmac_f32_e32 v64, v72, v72
	v_pk_add_f32 v[74:75], v[66:67], v[88:89]
	v_fmac_f32_e32 v64, v73, v73
	v_fmac_f32_e32 v64, v74, v74
	v_fmac_f32_e32 v64, v75, v75
	v_add_f32_e32 v64, v77, v64
	ds_bpermute_b32 v65, v120, v64
	global_store_dwordx4 v[90:91], v[68:71], off offset:512
	global_store_dwordx4 v[90:91], v[72:75], off offset:528
	v_cvt_pk_bf16_f32 v66, v68, v69
	v_cvt_pk_bf16_f32 v67, v70, v71
	s_waitcnt lgkmcnt(0)
	v_add_f32_e32 v64, v64, v65
	ds_bpermute_b32 v65, v114, v64
	v_cvt_pk_bf16_f32 v68, v72, v73
	v_cvt_pk_bf16_f32 v69, v74, v75
	global_store_dwordx4 v[94:95], v[66:69], off offset:256
	s_and_saveexec_b64 s[30:31], s[0:1]
	s_cbranch_execz .LBB0_675
	v_lshl_add_u64 v[66:67], v[80:81], 2, s[12:13]
	s_waitcnt lgkmcnt(0)
	v_add_f32_e32 v64, v64, v65
	global_atomic_add_f32 v[66:67], v64, off
; __device__ __forceinline__ unsigned cvt_pk_bf16(float lo, float hi) { unsigned r; asm volatile("v_cvt_pk_bf16_f32 %0, %1, %2" : "=v"(r) : "v"(lo), "v"(hi)); return r; }
;     __device__ __forceinline__ void operator()(const f32x4 (&acc)[2][2][4][2], const Unit& u, int wr, int wc, int fr, int fq) const {
;     ...
;             for (int m = 0; m < 4; ++m) { const size_t row = (size_t)(row0 + ai * HALF + m * 16); float ss = 0.f;
; #pragma unroll
;                 for (int bj = 0; bj < 2; ++bj) { const int col = u.pn * BM + bj * HALF + wc * 32 + 8 * fq;
;                     const float* xp = x + row * 2048 + col; float* hp = h1 + row * 2048 + col;
;                     const f32x4 a0 = *(const f32x4*)xp + acc[ai][bj][m][0], a1 = *(const f32x4*)(xp + 4) + acc[ai][bj][m][1];
;                     *(f32x4*)hp = a0; *(f32x4*)(hp + 4) = a1;
;                     ss += a0[0] * a0[0] + a0[1] * a0[1] + a0[2] * a0[2] + a0[3] * a0[3] + a1[0] * a1[0] + a1[1] * a1[1] + a1[2] * a1[2] + a1[3] * a1[3];
;                     u32x4 w; w.x = cvt_pk_bf16(a0[0], a0[1]); w.y = cvt_pk_bf16(a0[2], a0[3]); w.z = cvt_pk_bf16(a1[0], a1[1]); w.w = cvt_pk_bf16(a1[2], a1[3]);
;                     *(u32x4*)(h1b + row * 2048 + col) = w; }
;                 ss += __shfl_xor(ss, 16); ss += __shfl_xor(ss, 32);
;                 if (fq == 0) atomicAdd(rowsq + row, ss); }
.LBB0_675:
	s_or_b64 exec, exec, s[30:31]
	v_add_u32_e32 v64, 0x80, v148
	s_waitcnt lgkmcnt(0)
	v_ashrrev_i32_e32 v65, 31, v64
	v_lshlrev_b64 v[74:75], 13, v[64:65]
	v_lshl_add_u64 v[66:67], s[36:37], 0, v[74:75]
	v_lshl_add_u64 v[76:77], v[66:67], 0, v[146:147]
	global_load_dwordx4 v[66:69], v[76:77], off nt
	global_load_dwordx4 v[70:73], v[76:77], off offset:16 nt
	v_lshlrev_b64 v[78:79], 12, v[64:65]
	v_lshl_add_u64 v[74:75], s[26:27], 0, v[74:75]
	v_lshl_add_u64 v[78:79], s[10:11], 0, v[78:79]
	v_lshl_add_u64 v[74:75], v[74:75], 0, v[146:147]
	v_lshl_add_u64 v[78:79], v[144:145], 1, v[78:79]
	s_waitcnt vmcnt(1)
	v_pk_add_f32 v[62:63], v[62:63], v[68:69]
	v_pk_add_f32 v[60:61], v[60:61], v[66:67]
	s_waitcnt vmcnt(0)
	v_pk_add_f32 v[58:59], v[58:59], v[72:73]
	v_pk_add_f32 v[56:57], v[56:57], v[70:71]
	global_store_dwordx4 v[74:75], v[60:63], off
	global_store_dwordx4 v[74:75], v[56:59], off offset:16
	v_cvt_pk_bf16_f32 v66, v60, v61
	v_cvt_pk_bf16_f32 v67, v62, v63
	v_cvt_pk_bf16_f32 v68, v56, v57
	v_cvt_pk_bf16_f32 v69, v58, v59
	global_store_dwordx4 v[78:79], v[66:69], off
	global_load_dwordx4 v[66:69], v[76:77], off offset:512 nt
	s_nop 0
	global_load_dwordx4 v[70:73], v[76:77], off offset:528 nt
	v_mul_f32_e32 v61, v61, v61
	v_fmac_f32_e32 v61, v60, v60
	v_fmac_f32_e32 v61, v62, v62
	v_fmac_f32_e32 v61, v63, v63
	v_fmac_f32_e32 v61, v56, v56
	v_fmac_f32_e32 v61, v57, v57
	v_fmac_f32_e32 v61, v58, v58
	v_fmac_f32_e32 v61, v59, v59
	s_waitcnt vmcnt(1)
	v_pk_add_f32 v[52:53], v[52:53], v[66:67]
	s_waitcnt vmcnt(0)
	v_pk_add_f32 v[56:57], v[48:49], v[70:71]
	v_mul_f32_e32 v48, v53, v53
	v_pk_add_f32 v[54:55], v[54:55], v[68:69]
	v_fmac_f32_e32 v48, v52, v52
	v_fmac_f32_e32 v48, v54, v54
	v_fmac_f32_e32 v48, v55, v55
	v_fmac_f32_e32 v48, v56, v56
	v_pk_add_f32 v[58:59], v[50:51], v[72:73]
	v_fmac_f32_e32 v48, v57, v57
	v_fmac_f32_e32 v48, v58, v58
	v_fmac_f32_e32 v48, v59, v59
	v_add_f32_e32 v48, v61, v48
	ds_bpermute_b32 v49, v120, v48
	global_store_dwordx4 v[74:75], v[52:55], off offset:512
	global_store_dwordx4 v[74:75], v[56:59], off offset:528
	v_cvt_pk_bf16_f32 v50, v52, v53
	v_cvt_pk_bf16_f32 v51, v54, v55
	s_waitcnt lgkmcnt(0)
	v_add_f32_e32 v48, v48, v49
	ds_bpermute_b32 v49, v114, v48
	v_cvt_pk_bf16_f32 v52, v56, v57
	v_cvt_pk_bf16_f32 v53, v58, v59
	global_store_dwordx4 v[78:79], v[50:53], off offset:256
	s_and_saveexec_b64 s[30:31], s[0:1]
	s_cbranch_execz .LBB0_677
	v_lshl_add_u64 v[50:51], v[64:65], 2, s[12:13]
	s_waitcnt lgkmcnt(0)
	v_add_f32_e32 v48, v48, v49
	global_atomic_add_f32 v[50:51], v48, off
.LBB0_677:
	s_or_b64 exec, exec, s[30:31]
	v_add_u32_e32 v48, 0x90, v148
	s_waitcnt lgkmcnt(0)
	v_ashrrev_i32_e32 v49, 31, v48
	v_lshlrev_b64 v[58:59], 13, v[48:49]
	v_lshl_add_u64 v[50:51], s[36:37], 0, v[58:59]
	v_lshl_add_u64 v[60:61], v[50:51], 0, v[146:147]
	global_load_dwordx4 v[50:53], v[60:61], off nt
	global_load_dwordx4 v[54:57], v[60:61], off offset:16 nt
	v_lshlrev_b64 v[62:63], 12, v[48:49]
	v_lshl_add_u64 v[58:59], s[26:27], 0, v[58:59]
	v_lshl_add_u64 v[62:63], s[10:11], 0, v[62:63]
	v_lshl_add_u64 v[58:59], v[58:59], 0, v[146:147]
	v_lshl_add_u64 v[62:63], v[144:145], 1, v[62:63]
	s_waitcnt vmcnt(1)
	v_pk_add_f32 v[46:47], v[46:47], v[52:53]
	v_pk_add_f32 v[44:45], v[44:45], v[50:51]
	s_waitcnt vmcnt(0)
	v_pk_add_f32 v[42:43], v[42:43], v[56:57]
	v_pk_add_f32 v[40:41], v[40:41], v[54:55]
	global_store_dwordx4 v[58:59], v[44:47], off
	global_store_dwordx4 v[58:59], v[40:43], off offset:16
	v_cvt_pk_bf16_f32 v50, v44, v45
	v_cvt_pk_bf16_f32 v51, v46, v47
	v_cvt_pk_bf16_f32 v52, v40, v41
	v_cvt_pk_bf16_f32 v53, v42, v43
	global_store_dwordx4 v[62:63], v[50:53], off
	global_load_dwordx4 v[50:53], v[60:61], off offset:512 nt
	s_nop 0
	global_load_dwordx4 v[54:57], v[60:61], off offset:528 nt
	v_mul_f32_e32 v45, v45, v45
	v_fmac_f32_e32 v45, v44, v44
	v_fmac_f32_e32 v45, v46, v46
	v_fmac_f32_e32 v45, v47, v47
	v_fmac_f32_e32 v45, v40, v40
	v_fmac_f32_e32 v45, v41, v41
	v_fmac_f32_e32 v45, v42, v42
	v_fmac_f32_e32 v45, v43, v43
	s_waitcnt vmcnt(1)
	v_pk_add_f32 v[36:37], v[36:37], v[50:51]
	s_waitcnt vmcnt(0)
	v_pk_add_f32 v[40:41], v[32:33], v[54:55]
	v_mul_f32_e32 v32, v37, v37
	v_pk_add_f32 v[38:39], v[38:39], v[52:53]
	v_fmac_f32_e32 v32, v36, v36
	v_fmac_f32_e32 v32, v38, v38
	v_fmac_f32_e32 v32, v39, v39
	v_fmac_f32_e32 v32, v40, v40
	v_pk_add_f32 v[42:43], v[34:35], v[56:57]
	v_fmac_f32_e32 v32, v41, v41
	v_fmac_f32_e32 v32, v42, v42
	v_fmac_f32_e32 v32, v43, v43
	v_add_f32_e32 v32, v45, v32
	ds_bpermute_b32 v33, v120, v32
	global_store_dwordx4 v[58:59], v[36:39], off offset:512
	global_store_dwordx4 v[58:59], v[40:43], off offset:528
	v_cvt_pk_bf16_f32 v34, v36, v37
	v_cvt_pk_bf16_f32 v35, v38, v39
	s_waitcnt lgkmcnt(0)
	v_add_f32_e32 v32, v32, v33
	ds_bpermute_b32 v33, v114, v32
	v_cvt_pk_bf16_f32 v36, v40, v41
	v_cvt_pk_bf16_f32 v37, v42, v43
	global_store_dwordx4 v[62:63], v[34:37], off offset:256
	s_and_saveexec_b64 s[30:31], s[0:1]
	s_cbranch_execz .LBB0_679
	v_lshl_add_u64 v[34:35], v[48:49], 2, s[12:13]
	s_waitcnt lgkmcnt(0)
	v_add_f32_e32 v32, v32, v33
	global_atomic_add_f32 v[34:35], v32, off
; __device__ __forceinline__ unsigned cvt_pk_bf16(float lo, float hi) { unsigned r; asm volatile("v_cvt_pk_bf16_f32 %0, %1, %2" : "=v"(r) : "v"(lo), "v"(hi)); return r; }
;     __device__ __forceinline__ void operator()(const f32x4 (&acc)[2][2][4][2], const Unit& u, int wr, int wc, int fr, int fq) const {
;     ...
;             for (int m = 0; m < 4; ++m) { const size_t row = (size_t)(row0 + ai * HALF + m * 16); float ss = 0.f;
; #pragma unroll
;                 for (int bj = 0; bj < 2; ++bj) { const int col = u.pn * BM + bj * HALF + wc * 32 + 8 * fq;
;                     const float* xp = x + row * 2048 + col; float* hp = h1 + row * 2048 + col;
;                     const f32x4 a0 = *(const f32x4*)xp + acc[ai][bj][m][0], a1 = *(const f32x4*)(xp + 4) + acc[ai][bj][m][1];
;                     *(f32x4*)hp = a0; *(f32x4*)(hp + 4) = a1;
;                     ss += a0[0] * a0[0] + a0[1] * a0[1] + a0[2] * a0[2] + a0[3] * a0[3] + a1[0] * a1[0] + a1[1] * a1[1] + a1[2] * a1[2] + a1[3] * a1[3];
;                     u32x4 w; w.x = cvt_pk_bf16(a0[0], a0[1]); w.y = cvt_pk_bf16(a0[2], a0[3]); w.z = cvt_pk_bf16(a1[0], a1[1]); w.w = cvt_pk_bf16(a1[2], a1[3]);
;                     *(u32x4*)(h1b + row * 2048 + col) = w; }
;                 ss += __shfl_xor(ss, 16); ss += __shfl_xor(ss, 32);
;                 if (fq == 0) atomicAdd(rowsq + row, ss); }
.LBB0_679:
	s_or_b64 exec, exec, s[30:31]
	v_add_u32_e32 v32, 0xa0, v148
	s_waitcnt lgkmcnt(0)
	v_ashrrev_i32_e32 v33, 31, v32
	v_lshlrev_b64 v[42:43], 13, v[32:33]
	v_lshl_add_u64 v[34:35], s[36:37], 0, v[42:43]
	v_lshl_add_u64 v[44:45], v[34:35], 0, v[146:147]
	global_load_dwordx4 v[34:37], v[44:45], off nt
	global_load_dwordx4 v[38:41], v[44:45], off offset:16 nt
	v_lshlrev_b64 v[46:47], 12, v[32:33]
	v_lshl_add_u64 v[42:43], s[26:27], 0, v[42:43]
	v_lshl_add_u64 v[46:47], s[10:11], 0, v[46:47]
	v_lshl_add_u64 v[42:43], v[42:43], 0, v[146:147]
	v_lshl_add_u64 v[46:47], v[144:145], 1, v[46:47]
	s_waitcnt vmcnt(1)
	v_pk_add_f32 v[30:31], v[30:31], v[36:37]
	v_pk_add_f32 v[28:29], v[28:29], v[34:35]
	s_waitcnt vmcnt(0)
	v_pk_add_f32 v[26:27], v[26:27], v[40:41]
	v_pk_add_f32 v[24:25], v[24:25], v[38:39]
	global_store_dwordx4 v[42:43], v[28:31], off
	global_store_dwordx4 v[42:43], v[24:27], off offset:16
	v_cvt_pk_bf16_f32 v34, v28, v29
	v_cvt_pk_bf16_f32 v35, v30, v31
	v_cvt_pk_bf16_f32 v36, v24, v25
	v_cvt_pk_bf16_f32 v37, v26, v27
	global_store_dwordx4 v[46:47], v[34:37], off
	global_load_dwordx4 v[34:37], v[44:45], off offset:512 nt
	s_nop 0
	global_load_dwordx4 v[38:41], v[44:45], off offset:528 nt
	v_mul_f32_e32 v29, v29, v29
	v_fmac_f32_e32 v29, v28, v28
	v_fmac_f32_e32 v29, v30, v30
	v_fmac_f32_e32 v29, v31, v31
	v_fmac_f32_e32 v29, v24, v24
	v_fmac_f32_e32 v29, v25, v25
	v_fmac_f32_e32 v29, v26, v26
	v_fmac_f32_e32 v29, v27, v27
	s_waitcnt vmcnt(1)
	v_pk_add_f32 v[20:21], v[20:21], v[34:35]
	s_waitcnt vmcnt(0)
	v_pk_add_f32 v[24:25], v[16:17], v[38:39]
	v_mul_f32_e32 v16, v21, v21
	v_pk_add_f32 v[22:23], v[22:23], v[36:37]
	v_fmac_f32_e32 v16, v20, v20
	v_fmac_f32_e32 v16, v22, v22
	v_fmac_f32_e32 v16, v23, v23
	v_fmac_f32_e32 v16, v24, v24
	v_pk_add_f32 v[26:27], v[18:19], v[40:41]
	v_fmac_f32_e32 v16, v25, v25
	v_fmac_f32_e32 v16, v26, v26
	v_fmac_f32_e32 v16, v27, v27
	v_add_f32_e32 v16, v29, v16
	ds_bpermute_b32 v17, v120, v16
	global_store_dwordx4 v[42:43], v[20:23], off offset:512
	global_store_dwordx4 v[42:43], v[24:27], off offset:528
	v_cvt_pk_bf16_f32 v18, v20, v21
	v_cvt_pk_bf16_f32 v19, v22, v23
	s_waitcnt lgkmcnt(0)
	v_add_f32_e32 v16, v16, v17
	ds_bpermute_b32 v17, v114, v16
	v_cvt_pk_bf16_f32 v20, v24, v25
	v_cvt_pk_bf16_f32 v21, v26, v27
	global_store_dwordx4 v[46:47], v[18:21], off offset:256
	s_and_saveexec_b64 s[30:31], s[0:1]
	s_cbranch_execz .LBB0_681
	v_lshl_add_u64 v[18:19], v[32:33], 2, s[12:13]
	s_waitcnt lgkmcnt(0)
	v_add_f32_e32 v16, v16, v17
	global_atomic_add_f32 v[18:19], v16, off
.LBB0_681:
	s_or_b64 exec, exec, s[30:31]
	v_add_u32_e32 v16, 0xb0, v148
	s_waitcnt lgkmcnt(0)
	v_ashrrev_i32_e32 v17, 31, v16
	v_lshlrev_b64 v[26:27], 13, v[16:17]
	v_lshl_add_u64 v[18:19], s[36:37], 0, v[26:27]
	v_lshl_add_u64 v[28:29], v[18:19], 0, v[146:147]
	global_load_dwordx4 v[18:21], v[28:29], off nt
	global_load_dwordx4 v[22:25], v[28:29], off offset:16 nt
	v_lshlrev_b64 v[30:31], 12, v[16:17]
	v_lshl_add_u64 v[26:27], s[26:27], 0, v[26:27]
	v_lshl_add_u64 v[30:31], s[10:11], 0, v[30:31]
	v_lshl_add_u64 v[26:27], v[26:27], 0, v[146:147]
	v_lshl_add_u64 v[30:31], v[144:145], 1, v[30:31]
	s_waitcnt vmcnt(1)
	v_pk_add_f32 v[14:15], v[14:15], v[20:21]
	v_pk_add_f32 v[12:13], v[12:13], v[18:19]
	s_waitcnt vmcnt(0)
	v_pk_add_f32 v[10:11], v[10:11], v[24:25]
	v_pk_add_f32 v[8:9], v[8:9], v[22:23]
	global_store_dwordx4 v[26:27], v[12:15], off
	global_store_dwordx4 v[26:27], v[8:11], off offset:16
	v_cvt_pk_bf16_f32 v18, v12, v13
	v_cvt_pk_bf16_f32 v19, v14, v15
	v_cvt_pk_bf16_f32 v20, v8, v9
	v_cvt_pk_bf16_f32 v21, v10, v11
	global_store_dwordx4 v[30:31], v[18:21], off
	global_load_dwordx4 v[18:21], v[28:29], off offset:512 nt
	s_nop 0
	global_load_dwordx4 v[22:25], v[28:29], off offset:528 nt
	v_mul_f32_e32 v13, v13, v13
	v_fmac_f32_e32 v13, v12, v12
	v_fmac_f32_e32 v13, v14, v14
	v_fmac_f32_e32 v13, v15, v15
	v_fmac_f32_e32 v13, v8, v8
	v_fmac_f32_e32 v13, v9, v9
	v_fmac_f32_e32 v13, v10, v10
	v_fmac_f32_e32 v13, v11, v11
	s_waitcnt vmcnt(1)
	v_pk_add_f32 v[4:5], v[4:5], v[18:19]
	s_waitcnt vmcnt(0)
	v_pk_add_f32 v[8:9], v[0:1], v[22:23]
	v_mul_f32_e32 v0, v5, v5
	v_pk_add_f32 v[6:7], v[6:7], v[20:21]
	v_fmac_f32_e32 v0, v4, v4
	v_fmac_f32_e32 v0, v6, v6
	v_fmac_f32_e32 v0, v7, v7
	v_fmac_f32_e32 v0, v8, v8
	v_pk_add_f32 v[10:11], v[2:3], v[24:25]
	v_fmac_f32_e32 v0, v9, v9
	v_fmac_f32_e32 v0, v10, v10
	v_fmac_f32_e32 v0, v11, v11
	v_add_f32_e32 v0, v13, v0
	ds_bpermute_b32 v1, v120, v0
	global_store_dwordx4 v[26:27], v[4:7], off offset:512
	global_store_dwordx4 v[26:27], v[8:11], off offset:528
	v_cvt_pk_bf16_f32 v2, v4, v5
	v_cvt_pk_bf16_f32 v3, v6, v7
	s_waitcnt lgkmcnt(0)
	v_add_f32_e32 v0, v0, v1
	ds_bpermute_b32 v1, v114, v0
	v_cvt_pk_bf16_f32 v4, v8, v9
	v_cvt_pk_bf16_f32 v5, v10, v11
	global_store_dwordx4 v[30:31], v[2:5], off offset:256
	s_and_saveexec_b64 s[30:31], s[0:1]
	s_cbranch_execz .LBB0_683
	v_lshl_add_u64 v[2:3], v[16:17], 2, s[12:13]
	s_waitcnt lgkmcnt(0)
	v_add_f32_e32 v0, v0, v1
	global_atomic_add_f32 v[2:3], v0, off

;     __device__ __forceinline__ void operator()(const f32x4 (&acc)[2][2][4][2], const Unit& u, int wr, int wc, int fr, int fq) const {
;     ...
;             for (int m = 0; m < 4; ++m) { const size_t row = (size_t)(row0 + ai * HALF + m * 16);
; #pragma unroll
;                 for (int bj = 0; bj < 2; ++bj) { const int col = u.pn * BM + bj * HALF + wc * 32 + 8 * fq; float* op = out + row * 2048 + col;
;                     const f32x4 a0 = *(const f32x4*)op + acc[ai][bj][m][0], a1 = *(const f32x4*)(op + 4) + acc[ai][bj][m][1];
;                     *(f32x4*)op = a0; *(f32x4*)(op + 4) = a1; } }
.LBB0_745:
	v_lshl_add_u32 v146, s53, 8, v150
	v_lshl_or_b32 v144, s54, 8, v152
	v_ashrrev_i32_e32 v147, 31, v146
	v_lshlrev_b64 v[148:149], 13, v[146:147]
	v_ashrrev_i32_e32 v145, 31, v144
	v_lshl_add_u64 v[156:157], s[26:27], 0, v[148:149]
	v_lshlrev_b64 v[148:149], 2, v[144:145]
	v_lshl_add_u64 v[144:145], v[156:157], 0, v[148:149]
	global_load_dwordx4 v[156:159], v[144:145], off offset:16 nt
	global_load_dwordx4 v[160:163], v[144:145], off nt
	s_mov_b64 s[22:23], -1
	s_waitcnt vmcnt(0)
	v_pk_add_f32 v[122:123], v[122:123], v[158:159]
	v_pk_add_f32 v[126:127], v[126:127], v[162:163]
	v_pk_add_f32 v[124:125], v[124:125], v[160:161]
	v_pk_add_f32 v[120:121], v[120:121], v[156:157]
	global_store_dwordx4 v[144:145], v[124:127], off
	global_store_dwordx4 v[144:145], v[120:123], off offset:16
	global_load_dwordx4 v[120:123], v[144:145], off offset:528 nt
	s_nop 0
	global_load_dwordx4 v[124:127], v[144:145], off offset:512 nt
	s_waitcnt vmcnt(1)
	v_pk_add_f32 v[112:113], v[112:113], v[120:121]
	s_waitcnt vmcnt(0)
	v_pk_add_f32 v[118:119], v[118:119], v[126:127]
	v_pk_add_f32 v[116:117], v[116:117], v[124:125]
	v_pk_add_f32 v[114:115], v[114:115], v[122:123]
	global_store_dwordx4 v[144:145], v[116:119], off offset:512
	global_store_dwordx4 v[144:145], v[112:115], off offset:528
	s_nop 1
	v_or_b32_e32 v112, 16, v146
	v_ashrrev_i32_e32 v113, 31, v112
	v_lshlrev_b64 v[112:113], 13, v[112:113]
	v_lshl_add_u64 v[112:113], s[26:27], 0, v[112:113]
	v_lshl_add_u64 v[120:121], v[112:113], 0, v[148:149]
	global_load_dwordx4 v[112:115], v[120:121], off offset:16 nt
	global_load_dwordx4 v[116:119], v[120:121], off nt
	s_waitcnt vmcnt(1)
	v_pk_add_f32 v[106:107], v[106:107], v[114:115]
	s_waitcnt vmcnt(0)
	v_pk_add_f32 v[110:111], v[110:111], v[118:119]
	v_pk_add_f32 v[108:109], v[108:109], v[116:117]
	v_pk_add_f32 v[104:105], v[104:105], v[112:113]
	global_store_dwordx4 v[120:121], v[108:111], off
	global_store_dwordx4 v[120:121], v[104:107], off offset:16
	global_load_dwordx4 v[104:107], v[120:121], off offset:528 nt
	s_nop 0
	global_load_dwordx4 v[108:111], v[120:121], off offset:512 nt
	s_waitcnt vmcnt(1)
	v_pk_add_f32 v[96:97], v[96:97], v[104:105]
	s_waitcnt vmcnt(0)
	v_pk_add_f32 v[102:103], v[102:103], v[110:111]
	v_pk_add_f32 v[100:101], v[100:101], v[108:109]
	v_pk_add_f32 v[98:99], v[98:99], v[106:107]
	global_store_dwordx4 v[120:121], v[100:103], off offset:512
	global_store_dwordx4 v[120:121], v[96:99], off offset:528
	s_nop 1
	v_or_b32_e32 v96, 32, v146
	v_ashrrev_i32_e32 v97, 31, v96
	v_lshlrev_b64 v[96:97], 13, v[96:97]
	v_lshl_add_u64 v[96:97], s[26:27], 0, v[96:97]
	v_lshl_add_u64 v[104:105], v[96:97], 0, v[148:149]
	global_load_dwordx4 v[96:99], v[104:105], off offset:16 nt
	global_load_dwordx4 v[100:103], v[104:105], off nt
	s_waitcnt vmcnt(1)
	v_pk_add_f32 v[90:91], v[90:91], v[98:99]
	s_waitcnt vmcnt(0)
	v_pk_add_f32 v[94:95], v[94:95], v[102:103]
	v_pk_add_f32 v[92:93], v[92:93], v[100:101]
	v_pk_add_f32 v[88:89], v[88:89], v[96:97]
	global_store_dwordx4 v[104:105], v[92:95], off
	global_store_dwordx4 v[104:105], v[88:91], off offset:16
	global_load_dwordx4 v[88:91], v[104:105], off offset:528 nt
	s_nop 0
	global_load_dwordx4 v[92:95], v[104:105], off offset:512 nt
	s_waitcnt vmcnt(1)
	v_pk_add_f32 v[80:81], v[80:81], v[88:89]
	s_waitcnt vmcnt(0)
	v_pk_add_f32 v[86:87], v[86:87], v[94:95]
	v_pk_add_f32 v[84:85], v[84:85], v[92:93]
	v_pk_add_f32 v[82:83], v[82:83], v[90:91]
	global_store_dwordx4 v[104:105], v[84:87], off offset:512
	global_store_dwordx4 v[104:105], v[80:83], off offset:528
	s_nop 1
	v_or_b32_e32 v80, 48, v146
	v_ashrrev_i32_e32 v81, 31, v80
	v_lshlrev_b64 v[80:81], 13, v[80:81]
	v_lshl_add_u64 v[80:81], s[26:27], 0, v[80:81]
	v_lshl_add_u64 v[88:89], v[80:81], 0, v[148:149]
	global_load_dwordx4 v[80:83], v[88:89], off offset:16 nt
	global_load_dwordx4 v[84:87], v[88:89], off nt
	s_waitcnt vmcnt(1)
	v_pk_add_f32 v[74:75], v[74:75], v[82:83]
	s_waitcnt vmcnt(0)
	v_pk_add_f32 v[78:79], v[78:79], v[86:87]
	v_pk_add_f32 v[76:77], v[76:77], v[84:85]
	v_pk_add_f32 v[72:73], v[72:73], v[80:81]
	global_store_dwordx4 v[88:89], v[76:79], off
	global_store_dwordx4 v[88:89], v[72:75], off offset:16
	global_load_dwordx4 v[72:75], v[88:89], off offset:528 nt
	s_nop 0
	global_load_dwordx4 v[76:79], v[88:89], off offset:512 nt
	s_waitcnt vmcnt(1)
	v_pk_add_f32 v[66:67], v[66:67], v[74:75]
	s_waitcnt vmcnt(0)
;     __device__ __forceinline__ void operator()(const f32x4 (&acc)[2][2][4][2], const Unit& u, int wr, int wc, int fr, int fq) const {
;     ...
;             for (int m = 0; m < 4; ++m) { const size_t row = (size_t)(row0 + ai * HALF + m * 16);
; #pragma unroll
;                 for (int bj = 0; bj < 2; ++bj) { const int col = u.pn * BM + bj * HALF + wc * 32 + 8 * fq; float* op = out + row * 2048 + col;
;                     const f32x4 a0 = *(const f32x4*)op + acc[ai][bj][m][0], a1 = *(const f32x4*)(op + 4) + acc[ai][bj][m][1];
;                     *(f32x4*)op = a0; *(f32x4*)(op + 4) = a1; } }
	v_pk_add_f32 v[70:71], v[70:71], v[78:79]
	v_pk_add_f32 v[68:69], v[68:69], v[76:77]
	v_add_co_u32_e32 v74, vcc, s47, v144
	v_pk_add_f32 v[64:65], v[64:65], v[72:73]
	global_store_dwordx4 v[88:89], v[68:71], off offset:512
	global_store_dwordx4 v[88:89], v[64:67], off offset:528
	v_addc_co_u32_e32 v75, vcc, 0, v145, vcc
	v_lshl_add_u64 v[72:73], v[144:145], 0, s[14:15]
	global_load_dwordx4 v[64:67], v[74:75], off nt
	global_load_dwordx4 v[68:71], v[72:73], off offset:16 nt
	s_waitcnt vmcnt(1)
	v_pk_add_f32 v[62:63], v[62:63], v[66:67]
	v_pk_add_f32 v[60:61], v[60:61], v[64:65]
	s_waitcnt vmcnt(0)
	v_pk_add_f32 v[58:59], v[58:59], v[70:71]
	v_pk_add_f32 v[56:57], v[56:57], v[68:69]
	global_store_dwordx4 v[74:75], v[60:63], off
	global_store_dwordx4 v[72:73], v[56:59], off offset:16
	global_load_dwordx4 v[56:59], v[72:73], off offset:528 nt
	s_nop 0
	global_load_dwordx4 v[60:63], v[72:73], off offset:512 nt
	s_waitcnt vmcnt(1)
	v_pk_add_f32 v[50:51], v[50:51], v[58:59]
	s_waitcnt vmcnt(0)
	v_pk_add_f32 v[54:55], v[54:55], v[62:63]
	v_pk_add_f32 v[52:53], v[52:53], v[60:61]
	v_add_co_u32_e32 v58, vcc, s48, v144
	v_pk_add_f32 v[48:49], v[48:49], v[56:57]
	global_store_dwordx4 v[72:73], v[52:55], off offset:512
	global_store_dwordx4 v[72:73], v[48:51], off offset:528
	v_addc_co_u32_e32 v59, vcc, 0, v145, vcc
	v_lshl_add_u64 v[56:57], v[144:145], 0, s[16:17]
	global_load_dwordx4 v[48:51], v[58:59], off nt
	global_load_dwordx4 v[52:55], v[56:57], off offset:16 nt
	s_waitcnt vmcnt(1)
	v_pk_add_f32 v[46:47], v[46:47], v[50:51]
	v_pk_add_f32 v[44:45], v[44:45], v[48:49]
	s_waitcnt vmcnt(0)
	v_pk_add_f32 v[42:43], v[42:43], v[54:55]
	v_pk_add_f32 v[40:41], v[40:41], v[52:53]
	global_store_dwordx4 v[58:59], v[44:47], off
	global_store_dwordx4 v[56:57], v[40:43], off offset:16
	global_load_dwordx4 v[40:43], v[56:57], off offset:528 nt
	s_nop 0
	global_load_dwordx4 v[44:47], v[56:57], off offset:512 nt
	s_waitcnt vmcnt(1)
	v_pk_add_f32 v[34:35], v[34:35], v[42:43]
	s_waitcnt vmcnt(0)
	v_pk_add_f32 v[38:39], v[38:39], v[46:47]
	v_pk_add_f32 v[36:37], v[36:37], v[44:45]
	v_add_co_u32_e32 v42, vcc, s49, v144
	v_pk_add_f32 v[32:33], v[32:33], v[40:41]
	global_store_dwordx4 v[56:57], v[36:39], off offset:512
	global_store_dwordx4 v[56:57], v[32:35], off offset:528
	v_addc_co_u32_e32 v43, vcc, 0, v145, vcc
	v_lshl_add_u64 v[40:41], v[144:145], 0, s[18:19]
	global_load_dwordx4 v[32:35], v[42:43], off nt
	global_load_dwordx4 v[36:39], v[40:41], off offset:16 nt
	s_waitcnt vmcnt(1)
	v_pk_add_f32 v[30:31], v[30:31], v[34:35]
	v_pk_add_f32 v[28:29], v[28:29], v[32:33]
	s_waitcnt vmcnt(0)
	v_pk_add_f32 v[26:27], v[26:27], v[38:39]
	v_pk_add_f32 v[24:25], v[24:25], v[36:37]
	global_store_dwordx4 v[42:43], v[28:31], off
	global_store_dwordx4 v[40:41], v[24:27], off offset:16
	global_load_dwordx4 v[24:27], v[40:41], off offset:528 nt
	s_nop 0
	global_load_dwordx4 v[28:31], v[40:41], off offset:512 nt
	s_waitcnt vmcnt(1)
	v_pk_add_f32 v[18:19], v[18:19], v[26:27]
	s_waitcnt vmcnt(0)
	v_pk_add_f32 v[22:23], v[22:23], v[30:31]
	v_pk_add_f32 v[20:21], v[20:21], v[28:29]
	v_add_co_u32_e32 v26, vcc, s50, v144
	v_pk_add_f32 v[16:17], v[16:17], v[24:25]
	global_store_dwordx4 v[40:41], v[20:23], off offset:512
	global_store_dwordx4 v[40:41], v[16:19], off offset:528
	v_addc_co_u32_e32 v27, vcc, 0, v145, vcc
	s_nop 0
	v_lshl_add_u64 v[16:17], v[144:145], 0, s[6:7]
	global_load_dwordx4 v[18:21], v[26:27], off nt
	global_load_dwordx4 v[22:25], v[16:17], off offset:16 nt
	s_and_b64 vcc, exec, s[0:1]
	s_waitcnt vmcnt(1)
	v_pk_add_f32 v[14:15], v[14:15], v[20:21]
	v_pk_add_f32 v[12:13], v[12:13], v[18:19]
	s_waitcnt vmcnt(0)
	v_pk_add_f32 v[10:11], v[10:11], v[24:25]
	v_pk_add_f32 v[8:9], v[8:9], v[22:23]
	global_store_dwordx4 v[26:27], v[12:15], off
	global_store_dwordx4 v[16:17], v[8:11], off offset:16
	global_load_dwordx4 v[8:11], v[16:17], off offset:528 nt
	s_nop 0
	global_load_dwordx4 v[12:15], v[16:17], off offset:512 nt
	s_waitcnt vmcnt(1)
	v_pk_add_f32 v[2:3], v[2:3], v[10:11]
	s_waitcnt vmcnt(0)
	v_pk_add_f32 v[6:7], v[6:7], v[14:15]
	v_pk_add_f32 v[4:5], v[4:5], v[12:13]
	v_pk_add_f32 v[0:1], v[0:1], v[8:9]
	global_store_dwordx4 v[16:17], v[4:7], off offset:512
	global_store_dwordx4 v[16:17], v[0:3], off offset:528
	s_cbranch_vccnz .LBB0_730
	s_andn2_b64 vcc, exec, s[8:9]
	s_cbranch_vccnz .LBB0_729
	s_barrier
	s_branch .LBB0_729
